# scan loop head: step 0's sa reduction chain (state x prefetched kk0) issued right after the read burst, LDS-dependent ops after it
# speedup vs baseline: 1.0050x; 1.0046x over previous
.LBB0_1050:
	ds_read_b128 v[14:17], v0 offset:20480
	ds_read_b128 v[10:13], v0 offset:20496
	ds_read_b128 v[6:9], v0 offset:20512
	ds_read_b128 v[2:5], v0 offset:20528
	ds_read_b128 v[54:57], v89 offset:16384
	ds_read_b128 v[26:29], v89 offset:16640
	ds_read_b128 v[78:81], v89 offset:4096
	ds_read_b128 v[58:61], v89 offset:4352
	ds_read_b128 v[30:33], v89 offset:4608
	ds_read_b128 v[22:25], v90 offset:8704
	ds_read_b128 v[18:21], v89 offset:16896
	v_pk_mul_f32 v[66:67], v[74:75], v[108:109]
	v_pk_fma_f32 v[66:67], v[76:77], v[110:111], v[66:67]
	s_add_i32 s26, s26, 1
	v_add_f32_e32 v66, v66, v67
	s_nop 1
	v_add_f32_dpp v66, v66, v66 quad_perm:[1,0,3,2] row_mask:0xf bank_mask:0xf bound_ctrl:1
	s_nop 1
	v_add_f32_dpp v66, v66, v66 quad_perm:[2,3,0,1] row_mask:0xf bank_mask:0xf bound_ctrl:1
	s_nop 1
	v_add_f32_dpp v66, v66, v66 row_half_mirror row_mask:0xf bank_mask:0xf bound_ctrl:1
	s_waitcnt lgkmcnt(4)
	v_pk_mul_f32 v[78:79], v[14:15], v[78:79] op_sel_hi:[0,1]
	v_pk_mul_f32 v[80:81], v[14:15], v[80:81] op_sel_hi:[0,1]
	v_add_f32_dpp v66, v66, v66 row_ror:8 row_mask:0xf bank_mask:0xf bound_ctrl:1
	v_pk_fma_f32 v[62:63], v[74:75], v[100:101], v[78:79]
	v_pk_fma_f32 v[64:65], v[76:77], v[102:103], v[80:81]
	v_mov_b32_e32 v0, v17
	v_mov_b32_e32 v82, v13
	v_mov_b32_e32 v84, v9
	v_mov_b32_e32 v86, v5
	v_pk_fma_f32 v[62:63], v[120:121], v[66:67], v[62:63] op_sel_hi:[1,0,1] neg_lo:[1,0,0] neg_hi:[1,0,0]
	v_pk_fma_f32 v[64:65], v[122:123], v[66:67], v[64:65] op_sel_hi:[1,0,1] neg_lo:[1,0,0] neg_hi:[1,0,0]
	v_pk_mul_f32 v[50:51], v[112:113], v[62:63]
	v_pk_mul_f32 v[46:47], v[104:105], v[62:63]
	v_pk_fma_f32 v[50:51], v[114:115], v[64:65], v[50:51]
	s_waitcnt lgkmcnt(3)
	v_pk_fma_f32 v[66:67], v[14:15], v[58:59], v[46:47] op_sel:[1,0,0]
	v_add_f32_e32 v47, v50, v51
	v_pk_mul_f32 v[48:49], v[106:107], v[64:65]
	v_pk_mul_f32 v[56:57], v[56:57], v[64:65]
	v_add_f32_dpp v68, v47, v47 quad_perm:[1,0,3,2] row_mask:0xf bank_mask:0xf bound_ctrl:1
	v_pk_fma_f32 v[14:15], v[14:15], v[60:61], v[48:49] op_sel:[1,0,0]
	v_pk_fma_f32 v[54:55], v[54:55], v[62:63], v[56:57]
	v_add_f32_dpp v68, v68, v68 quad_perm:[2,3,0,1] row_mask:0xf bank_mask:0xf bound_ctrl:1
	v_add_f32_e32 v92, v54, v55
	s_nop 0
	v_add_f32_dpp v68, v68, v68 row_half_mirror row_mask:0xf bank_mask:0xf bound_ctrl:1
	ds_read_b128 v[46:49], v90 offset:768
	ds_read_b128 v[50:53], v89 offset:4864
	ds_read_b128 v[54:57], v90 offset:4864
	ds_read_b128 v[58:61], v90 offset:8960
	ds_read_b128 v[62:65], v89 offset:17152
	v_add_f32_dpp v68, v68, v68 row_ror:8 row_mask:0xf bank_mask:0xf bound_ctrl:1
	v_pk_fma_f32 v[42:43], v[128:129], v[68:69], v[66:67] op_sel_hi:[1,0,1] neg_lo:[1,0,0] neg_hi:[1,0,0]
	v_pk_fma_f32 v[14:15], v[130:131], v[68:69], v[14:15] op_sel_hi:[1,0,1] neg_lo:[1,0,0] neg_hi:[1,0,0]
	v_pk_mul_f32 v[38:39], v[124:125], v[42:43]
	v_pk_mul_f32 v[28:29], v[28:29], v[14:15]
	v_pk_mul_f32 v[36:37], v[118:119], v[14:15]
	v_pk_fma_f32 v[14:15], v[126:127], v[14:15], v[38:39]
	v_pk_mul_f32 v[34:35], v[116:117], v[42:43]
	v_add_f32_e32 v14, v14, v15
	v_pk_fma_f32 v[26:27], v[26:27], v[42:43], v[28:29]
	s_waitcnt lgkmcnt(7)
	v_pk_fma_f32 v[42:43], v[16:17], v[30:31], v[34:35] op_sel_hi:[0,1,1]
	v_add_f32_dpp v66, v14, v14 quad_perm:[1,0,3,2] row_mask:0xf bank_mask:0xf bound_ctrl:1
	v_pk_fma_f32 v[44:45], v[16:17], v[32:33], v[36:37] op_sel_hi:[0,1,1]
	v_add_f32_e32 v93, v26, v27
	v_add_f32_dpp v66, v66, v66 quad_perm:[2,3,0,1] row_mask:0xf bank_mask:0xf bound_ctrl:1
	ds_read_b128 v[14:17], v90 offset:1024
	ds_read_b128 v[26:29], v89 offset:5120
	ds_read_b128 v[30:33], v90 offset:5120
	ds_read_b128 v[34:37], v90 offset:9216
	ds_read_b128 v[38:41], v89 offset:17408
	v_add_f32_dpp v66, v66, v66 row_half_mirror row_mask:0xf bank_mask:0xf bound_ctrl:1
	s_nop 1
	v_add_f32_dpp v66, v66, v66 row_ror:8 row_mask:0xf bank_mask:0xf bound_ctrl:1
	s_waitcnt lgkmcnt(11)
	v_pk_fma_f32 v[22:23], v[22:23], v[66:67], v[42:43] op_sel_hi:[1,0,1] neg_lo:[1,0,0] neg_hi:[1,0,0]
	v_pk_fma_f32 v[24:25], v[24:25], v[66:67], v[44:45] op_sel_hi:[1,0,1] neg_lo:[1,0,0] neg_hi:[1,0,0]
	s_waitcnt lgkmcnt(7)
	v_pk_mul_f32 v[42:43], v[54:55], v[22:23]
	v_pk_mul_f32 v[20:21], v[20:21], v[24:25]
	v_pk_mul_f32 v[44:45], v[46:47], v[22:23]
	v_pk_mul_f32 v[46:47], v[48:49], v[24:25]
	v_pk_fma_f32 v[18:19], v[18:19], v[22:23], v[20:21]
	v_pk_fma_f32 v[20:21], v[56:57], v[24:25], v[42:43]
	v_pk_fma_f32 v[54:55], v[0:1], v[50:51], v[44:45] op_sel_hi:[0,1,1]
	v_pk_fma_f32 v[56:57], v[0:1], v[52:53], v[46:47] op_sel_hi:[0,1,1]
	v_add_f32_e32 v94, v18, v19
	v_add_f32_e32 v18, v20, v21
	s_nop 0
	s_nop 0
	v_add_f32_dpp v0, v18, v18 quad_perm:[1,0,3,2] row_mask:0xf bank_mask:0xf bound_ctrl:1
	ds_read_b128 v[18:21], v90 offset:1280
	ds_read_b128 v[22:25], v89 offset:5376
	v_add_f32_dpp v0, v0, v0 quad_perm:[2,3,0,1] row_mask:0xf bank_mask:0xf bound_ctrl:1
	ds_read_b128 v[42:45], v90 offset:5376
	ds_read_b128 v[46:49], v90 offset:9472
	v_add_f32_dpp v0, v0, v0 row_half_mirror row_mask:0xf bank_mask:0xf bound_ctrl:1
	ds_read_b128 v[50:53], v89 offset:17664
	s_nop 0
	v_add_f32_dpp v0, v0, v0 row_ror:8 row_mask:0xf bank_mask:0xf bound_ctrl:1
	s_waitcnt lgkmcnt(11)
	v_pk_fma_f32 v[54:55], v[58:59], v[0:1], v[54:55] op_sel_hi:[1,0,1] neg_lo:[1,0,0] neg_hi:[1,0,0]
	v_pk_fma_f32 v[56:57], v[60:61], v[0:1], v[56:57] op_sel_hi:[1,0,1] neg_lo:[1,0,0] neg_hi:[1,0,0]
	s_waitcnt lgkmcnt(7)
	v_pk_mul_f32 v[30:31], v[30:31], v[54:55]
	v_pk_mul_f32 v[58:59], v[64:65], v[56:57]
	v_pk_mul_f32 v[14:15], v[14:15], v[54:55]
	v_pk_fma_f32 v[54:55], v[62:63], v[54:55], v[58:59]
	v_pk_fma_f32 v[30:31], v[32:33], v[56:57], v[30:31]
	v_pk_fma_f32 v[62:63], v[10:11], v[26:27], v[14:15] op_sel_hi:[0,1,1]
	v_add_f32_e32 v95, v54, v55
	v_add_f32_e32 v14, v30, v31
	ds_write_b128 v91, v[92:95] offset:43008
	v_pk_mul_f32 v[16:17], v[16:17], v[56:57]
	v_add_f32_dpp v0, v14, v14 quad_perm:[1,0,3,2] row_mask:0xf bank_mask:0xf bound_ctrl:1
	v_pk_fma_f32 v[64:65], v[10:11], v[28:29], v[16:17] op_sel_hi:[0,1,1]
	ds_read_b128 v[14:17], v90 offset:1536
	v_add_f32_dpp v0, v0, v0 quad_perm:[2,3,0,1] row_mask:0xf bank_mask:0xf bound_ctrl:1
	ds_read_b128 v[26:29], v89 offset:5632
	ds_read_b128 v[30:33], v90 offset:5632
	v_add_f32_dpp v0, v0, v0 row_half_mirror row_mask:0xf bank_mask:0xf bound_ctrl:1
	ds_read_b128 v[54:57], v90 offset:9728
	ds_read_b128 v[58:61], v89 offset:17920
	v_add_f32_dpp v0, v0, v0 row_ror:8 row_mask:0xf bank_mask:0xf bound_ctrl:1
	s_waitcnt lgkmcnt(12)
	v_pk_fma_f32 v[34:35], v[34:35], v[0:1], v[62:63] op_sel_hi:[1,0,1] neg_lo:[1,0,0] neg_hi:[1,0,0]
	v_pk_fma_f32 v[36:37], v[36:37], v[0:1], v[64:65] op_sel_hi:[1,0,1] neg_lo:[1,0,0] neg_hi:[1,0,0]
	s_waitcnt lgkmcnt(8)
	v_pk_mul_f32 v[42:43], v[42:43], v[34:35]
	v_pk_mul_f32 v[40:41], v[40:41], v[36:37]
	v_pk_mul_f32 v[18:19], v[18:19], v[34:35]
	v_pk_mul_f32 v[20:21], v[20:21], v[36:37]
	v_pk_fma_f32 v[34:35], v[38:39], v[34:35], v[40:41]
	v_pk_fma_f32 v[36:37], v[44:45], v[36:37], v[42:43]
	v_pk_fma_f32 v[62:63], v[10:11], v[22:23], v[18:19] op_sel:[1,0,0]
	v_add_f32_e32 v18, v36, v37
	v_add_f32_e32 v96, v34, v35
	v_pk_fma_f32 v[10:11], v[10:11], v[24:25], v[20:21] op_sel:[1,0,0]
	v_add_f32_dpp v0, v18, v18 quad_perm:[1,0,3,2] row_mask:0xf bank_mask:0xf bound_ctrl:1
	ds_read_b128 v[18:21], v90 offset:1792
	ds_read_b128 v[22:25], v89 offset:5888
	v_add_f32_dpp v0, v0, v0 quad_perm:[2,3,0,1] row_mask:0xf bank_mask:0xf bound_ctrl:1
	ds_read_b128 v[34:37], v90 offset:5888
	ds_read_b128 v[38:41], v90 offset:9984
	v_add_f32_dpp v0, v0, v0 row_half_mirror row_mask:0xf bank_mask:0xf bound_ctrl:1
	ds_read_b128 v[42:45], v89 offset:18176
	s_nop 0
	v_add_f32_dpp v0, v0, v0 row_ror:8 row_mask:0xf bank_mask:0xf bound_ctrl:1
	s_waitcnt lgkmcnt(12)
	v_pk_fma_f32 v[46:47], v[46:47], v[0:1], v[62:63] op_sel_hi:[1,0,1] neg_lo:[1,0,0] neg_hi:[1,0,0]
	v_pk_fma_f32 v[10:11], v[48:49], v[0:1], v[10:11] op_sel_hi:[1,0,1] neg_lo:[1,0,0] neg_hi:[1,0,0]
	s_waitcnt lgkmcnt(7)
	v_pk_mul_f32 v[30:31], v[30:31], v[46:47]
	v_pk_mul_f32 v[48:49], v[52:53], v[10:11]
	v_pk_mul_f32 v[14:15], v[14:15], v[46:47]
	v_pk_mul_f32 v[16:17], v[16:17], v[10:11]
	v_pk_fma_f32 v[46:47], v[50:51], v[46:47], v[48:49]
	v_pk_fma_f32 v[10:11], v[32:33], v[10:11], v[30:31]
	v_add_f32_e32 v10, v10, v11
	v_add_f32_e32 v97, v46, v47
	v_pk_fma_f32 v[50:51], v[12:13], v[26:27], v[14:15] op_sel_hi:[0,1,1]
	v_add_f32_dpp v0, v10, v10 quad_perm:[1,0,3,2] row_mask:0xf bank_mask:0xf bound_ctrl:1
	v_pk_fma_f32 v[52:53], v[12:13], v[28:29], v[16:17] op_sel_hi:[0,1,1]
	ds_read_b128 v[10:13], v90 offset:2048
	v_add_f32_dpp v0, v0, v0 quad_perm:[2,3,0,1] row_mask:0xf bank_mask:0xf bound_ctrl:1
	ds_read_b128 v[14:17], v89 offset:6144
	ds_read_b128 v[26:29], v90 offset:6144
	v_add_f32_dpp v0, v0, v0 row_half_mirror row_mask:0xf bank_mask:0xf bound_ctrl:1
	ds_read_b128 v[30:33], v90 offset:10240
	ds_read_b128 v[46:49], v89 offset:18432
	v_add_f32_dpp v0, v0, v0 row_ror:8 row_mask:0xf bank_mask:0xf bound_ctrl:1
	s_waitcnt lgkmcnt(11)
	v_pk_fma_f32 v[50:51], v[54:55], v[0:1], v[50:51] op_sel_hi:[1,0,1] neg_lo:[1,0,0] neg_hi:[1,0,0]
	v_pk_fma_f32 v[52:53], v[56:57], v[0:1], v[52:53] op_sel_hi:[1,0,1] neg_lo:[1,0,0] neg_hi:[1,0,0]
	s_waitcnt lgkmcnt(7)
	v_pk_mul_f32 v[34:35], v[34:35], v[50:51]
	v_pk_mul_f32 v[54:55], v[60:61], v[52:53]
	v_pk_mul_f32 v[18:19], v[18:19], v[50:51]
	v_pk_fma_f32 v[50:51], v[58:59], v[50:51], v[54:55]
	v_pk_fma_f32 v[34:35], v[36:37], v[52:53], v[34:35]
	v_pk_fma_f32 v[58:59], v[82:83], v[22:23], v[18:19] op_sel_hi:[0,1,1]
	v_add_f32_e32 v18, v34, v35
	v_add_f32_e32 v98, v50, v51
	v_pk_mul_f32 v[20:21], v[20:21], v[52:53]
	v_add_f32_dpp v0, v18, v18 quad_perm:[1,0,3,2] row_mask:0xf bank_mask:0xf bound_ctrl:1
	v_pk_fma_f32 v[60:61], v[82:83], v[24:25], v[20:21] op_sel_hi:[0,1,1]
	ds_read_b128 v[18:21], v90 offset:2304
	v_add_f32_dpp v0, v0, v0 quad_perm:[2,3,0,1] row_mask:0xf bank_mask:0xf bound_ctrl:1
	ds_read_b128 v[22:25], v89 offset:6400
	ds_read_b128 v[34:37], v90 offset:6400
	v_add_f32_dpp v0, v0, v0 row_half_mirror row_mask:0xf bank_mask:0xf bound_ctrl:1
	ds_read_b128 v[50:53], v90 offset:10496
	ds_read_b128 v[54:57], v89 offset:18688
	v_add_f32_dpp v0, v0, v0 row_ror:8 row_mask:0xf bank_mask:0xf bound_ctrl:1
	s_waitcnt lgkmcnt(11)
	v_pk_fma_f32 v[38:39], v[38:39], v[0:1], v[58:59] op_sel_hi:[1,0,1] neg_lo:[1,0,0] neg_hi:[1,0,0]
	v_pk_fma_f32 v[40:41], v[40:41], v[0:1], v[60:61] op_sel_hi:[1,0,1] neg_lo:[1,0,0] neg_hi:[1,0,0]
	s_waitcnt lgkmcnt(7)
	v_pk_mul_f32 v[26:27], v[26:27], v[38:39]
	v_pk_mul_f32 v[44:45], v[44:45], v[40:41]
	v_pk_mul_f32 v[10:11], v[10:11], v[38:39]
	v_pk_fma_f32 v[38:39], v[42:43], v[38:39], v[44:45]
	v_pk_fma_f32 v[26:27], v[28:29], v[40:41], v[26:27]
	v_pk_fma_f32 v[58:59], v[6:7], v[14:15], v[10:11] op_sel_hi:[0,1,1]
	v_add_f32_e32 v99, v38, v39
	v_add_f32_e32 v10, v26, v27
	ds_write_b128 v91, v[96:99] offset:47104
	v_pk_mul_f32 v[12:13], v[12:13], v[40:41]
	v_add_f32_dpp v0, v10, v10 quad_perm:[1,0,3,2] row_mask:0xf bank_mask:0xf bound_ctrl:1
	v_pk_fma_f32 v[60:61], v[6:7], v[16:17], v[12:13] op_sel_hi:[0,1,1]
	ds_read_b128 v[10:13], v90 offset:2560
	v_add_f32_dpp v0, v0, v0 quad_perm:[2,3,0,1] row_mask:0xf bank_mask:0xf bound_ctrl:1
	ds_read_b128 v[14:17], v89 offset:6656
	ds_read_b128 v[26:29], v90 offset:6656
	v_add_f32_dpp v0, v0, v0 row_half_mirror row_mask:0xf bank_mask:0xf bound_ctrl:1
	ds_read_b128 v[38:41], v90 offset:10752
	ds_read_b128 v[42:45], v89 offset:18944
	v_add_f32_dpp v0, v0, v0 row_ror:8 row_mask:0xf bank_mask:0xf bound_ctrl:1
	s_waitcnt lgkmcnt(12)
	v_pk_fma_f32 v[30:31], v[30:31], v[0:1], v[58:59] op_sel_hi:[1,0,1] neg_lo:[1,0,0] neg_hi:[1,0,0]
	v_pk_fma_f32 v[32:33], v[32:33], v[0:1], v[60:61] op_sel_hi:[1,0,1] neg_lo:[1,0,0] neg_hi:[1,0,0]
	s_waitcnt lgkmcnt(8)
	v_pk_mul_f32 v[34:35], v[34:35], v[30:31]
	v_pk_mul_f32 v[48:49], v[48:49], v[32:33]
	v_pk_mul_f32 v[18:19], v[18:19], v[30:31]
	v_pk_mul_f32 v[20:21], v[20:21], v[32:33]
	v_pk_fma_f32 v[30:31], v[46:47], v[30:31], v[48:49]
	v_pk_fma_f32 v[32:33], v[36:37], v[32:33], v[34:35]
	v_pk_fma_f32 v[58:59], v[6:7], v[22:23], v[18:19] op_sel:[1,0,0]
	v_add_f32_e32 v18, v32, v33
	v_add_f32_e32 v92, v30, v31
	v_pk_fma_f32 v[6:7], v[6:7], v[24:25], v[20:21] op_sel:[1,0,0]
	v_add_f32_dpp v0, v18, v18 quad_perm:[1,0,3,2] row_mask:0xf bank_mask:0xf bound_ctrl:1
	ds_read_b128 v[18:21], v90 offset:2816
	ds_read_b128 v[22:25], v89 offset:6912
	v_add_f32_dpp v0, v0, v0 quad_perm:[2,3,0,1] row_mask:0xf bank_mask:0xf bound_ctrl:1
	ds_read_b128 v[30:33], v90 offset:6912
	ds_read_b128 v[34:37], v90 offset:11008
	v_add_f32_dpp v0, v0, v0 row_half_mirror row_mask:0xf bank_mask:0xf bound_ctrl:1
	ds_read_b128 v[46:49], v89 offset:19200
	s_nop 0
	v_add_f32_dpp v0, v0, v0 row_ror:8 row_mask:0xf bank_mask:0xf bound_ctrl:1
	s_waitcnt lgkmcnt(12)
	v_pk_fma_f32 v[50:51], v[50:51], v[0:1], v[58:59] op_sel_hi:[1,0,1] neg_lo:[1,0,0] neg_hi:[1,0,0]
	v_pk_fma_f32 v[6:7], v[52:53], v[0:1], v[6:7] op_sel_hi:[1,0,1] neg_lo:[1,0,0] neg_hi:[1,0,0]
	s_waitcnt lgkmcnt(7)
	v_pk_mul_f32 v[26:27], v[26:27], v[50:51]
	v_pk_mul_f32 v[52:53], v[56:57], v[6:7]
	v_pk_mul_f32 v[10:11], v[10:11], v[50:51]
	v_pk_mul_f32 v[12:13], v[12:13], v[6:7]
	v_pk_fma_f32 v[50:51], v[54:55], v[50:51], v[52:53]
	v_pk_fma_f32 v[6:7], v[28:29], v[6:7], v[26:27]
	v_add_f32_e32 v6, v6, v7
	v_add_f32_e32 v93, v50, v51
	v_pk_fma_f32 v[54:55], v[8:9], v[14:15], v[10:11] op_sel_hi:[0,1,1]
	v_add_f32_dpp v0, v6, v6 quad_perm:[1,0,3,2] row_mask:0xf bank_mask:0xf bound_ctrl:1
	v_pk_fma_f32 v[56:57], v[8:9], v[16:17], v[12:13] op_sel_hi:[0,1,1]
	ds_read_b128 v[6:9], v90 offset:3072
	v_add_f32_dpp v0, v0, v0 quad_perm:[2,3,0,1] row_mask:0xf bank_mask:0xf bound_ctrl:1
	ds_read_b128 v[10:13], v89 offset:7168
	ds_read_b128 v[14:17], v90 offset:7168
	v_add_f32_dpp v0, v0, v0 row_half_mirror row_mask:0xf bank_mask:0xf bound_ctrl:1
	ds_read_b128 v[26:29], v90 offset:11264
	ds_read_b128 v[50:53], v89 offset:19456
	v_add_f32_dpp v0, v0, v0 row_ror:8 row_mask:0xf bank_mask:0xf bound_ctrl:1
	s_waitcnt lgkmcnt(11)
	v_pk_fma_f32 v[38:39], v[38:39], v[0:1], v[54:55] op_sel_hi:[1,0,1] neg_lo:[1,0,0] neg_hi:[1,0,0]
	v_pk_fma_f32 v[40:41], v[40:41], v[0:1], v[56:57] op_sel_hi:[1,0,1] neg_lo:[1,0,0] neg_hi:[1,0,0]
	s_waitcnt lgkmcnt(7)
	v_pk_mul_f32 v[30:31], v[30:31], v[38:39]
	v_pk_mul_f32 v[44:45], v[44:45], v[40:41]
	v_pk_mul_f32 v[18:19], v[18:19], v[38:39]
	v_pk_fma_f32 v[38:39], v[42:43], v[38:39], v[44:45]
	v_pk_fma_f32 v[30:31], v[32:33], v[40:41], v[30:31]
	v_pk_fma_f32 v[54:55], v[84:85], v[22:23], v[18:19] op_sel_hi:[0,1,1]
	v_add_f32_e32 v18, v30, v31
	v_add_f32_e32 v94, v38, v39
	v_pk_mul_f32 v[20:21], v[20:21], v[40:41]
	v_add_f32_dpp v0, v18, v18 quad_perm:[1,0,3,2] row_mask:0xf bank_mask:0xf bound_ctrl:1
	v_pk_fma_f32 v[56:57], v[84:85], v[24:25], v[20:21] op_sel_hi:[0,1,1]
	ds_read_b128 v[18:21], v90 offset:3328
	v_add_f32_dpp v0, v0, v0 quad_perm:[2,3,0,1] row_mask:0xf bank_mask:0xf bound_ctrl:1
	ds_read_b128 v[22:25], v89 offset:7424
	ds_read_b128 v[30:33], v90 offset:7424
	v_add_f32_dpp v0, v0, v0 row_half_mirror row_mask:0xf bank_mask:0xf bound_ctrl:1
	ds_read_b128 v[38:41], v90 offset:11520
	ds_read_b128 v[42:45], v89 offset:19712
	v_add_f32_dpp v0, v0, v0 row_ror:8 row_mask:0xf bank_mask:0xf bound_ctrl:1
	s_waitcnt lgkmcnt(11)
	v_pk_fma_f32 v[34:35], v[34:35], v[0:1], v[54:55] op_sel_hi:[1,0,1] neg_lo:[1,0,0] neg_hi:[1,0,0]
	v_pk_fma_f32 v[36:37], v[36:37], v[0:1], v[56:57] op_sel_hi:[1,0,1] neg_lo:[1,0,0] neg_hi:[1,0,0]
	s_waitcnt lgkmcnt(7)
	v_pk_mul_f32 v[14:15], v[14:15], v[34:35]
	v_pk_mul_f32 v[48:49], v[48:49], v[36:37]
	v_pk_mul_f32 v[6:7], v[6:7], v[34:35]
	v_pk_fma_f32 v[34:35], v[46:47], v[34:35], v[48:49]
	v_pk_fma_f32 v[14:15], v[16:17], v[36:37], v[14:15]
	v_pk_fma_f32 v[54:55], v[2:3], v[10:11], v[6:7] op_sel_hi:[0,1,1]
	v_add_f32_e32 v95, v34, v35
	v_add_f32_e32 v6, v14, v15
	ds_write_b128 v91, v[92:95] offset:51200
	v_pk_mul_f32 v[8:9], v[8:9], v[36:37]
	v_add_f32_dpp v0, v6, v6 quad_perm:[1,0,3,2] row_mask:0xf bank_mask:0xf bound_ctrl:1
	v_pk_fma_f32 v[56:57], v[2:3], v[12:13], v[8:9] op_sel_hi:[0,1,1]
	ds_read_b128 v[6:9], v90 offset:3584
	v_add_f32_dpp v0, v0, v0 quad_perm:[2,3,0,1] row_mask:0xf bank_mask:0xf bound_ctrl:1
	ds_read_b128 v[10:13], v89 offset:7680
	ds_read_b128 v[14:17], v90 offset:7680
	v_add_f32_dpp v0, v0, v0 row_half_mirror row_mask:0xf bank_mask:0xf bound_ctrl:1
	ds_read_b128 v[34:37], v90 offset:11776
	ds_read_b128 v[46:49], v89 offset:19968
	v_add_f32_dpp v0, v0, v0 row_ror:8 row_mask:0xf bank_mask:0xf bound_ctrl:1
	s_waitcnt lgkmcnt(12)
	v_pk_fma_f32 v[26:27], v[26:27], v[0:1], v[54:55] op_sel_hi:[1,0,1] neg_lo:[1,0,0] neg_hi:[1,0,0]
	v_pk_fma_f32 v[28:29], v[28:29], v[0:1], v[56:57] op_sel_hi:[1,0,1] neg_lo:[1,0,0] neg_hi:[1,0,0]
	s_waitcnt lgkmcnt(8)
	v_pk_mul_f32 v[30:31], v[30:31], v[26:27]
	v_pk_mul_f32 v[52:53], v[52:53], v[28:29]
	v_pk_mul_f32 v[18:19], v[18:19], v[26:27]
	v_pk_mul_f32 v[20:21], v[20:21], v[28:29]
	v_pk_fma_f32 v[26:27], v[50:51], v[26:27], v[52:53]
	v_pk_fma_f32 v[28:29], v[32:33], v[28:29], v[30:31]
	v_pk_fma_f32 v[54:55], v[2:3], v[22:23], v[18:19] op_sel:[1,0,0]
	v_add_f32_e32 v18, v28, v29
	v_add_f32_e32 v96, v26, v27
	v_pk_fma_f32 v[2:3], v[2:3], v[24:25], v[20:21] op_sel:[1,0,0]
	v_add_f32_dpp v0, v18, v18 quad_perm:[1,0,3,2] row_mask:0xf bank_mask:0xf bound_ctrl:1
	ds_read_b128 v[18:21], v90 offset:3840
	ds_read_b128 v[22:25], v89 offset:7936
	v_add_f32_dpp v0, v0, v0 quad_perm:[2,3,0,1] row_mask:0xf bank_mask:0xf bound_ctrl:1
	ds_read_b128 v[26:29], v90 offset:7936
	ds_read_b128 v[30:33], v90 offset:12032
	v_add_f32_dpp v0, v0, v0 row_half_mirror row_mask:0xf bank_mask:0xf bound_ctrl:1
	ds_read_b128 v[50:53], v89 offset:20224
	s_nop 0
	v_add_f32_dpp v0, v0, v0 row_ror:8 row_mask:0xf bank_mask:0xf bound_ctrl:1
	s_waitcnt lgkmcnt(12)
	v_pk_fma_f32 v[38:39], v[38:39], v[0:1], v[54:55] op_sel_hi:[1,0,1] neg_lo:[1,0,0] neg_hi:[1,0,0]
	v_pk_fma_f32 v[2:3], v[40:41], v[0:1], v[2:3] op_sel_hi:[1,0,1] neg_lo:[1,0,0] neg_hi:[1,0,0]
	s_waitcnt lgkmcnt(7)
	v_pk_mul_f32 v[14:15], v[14:15], v[38:39]
	v_pk_mul_f32 v[40:41], v[44:45], v[2:3]
	v_pk_mul_f32 v[8:9], v[8:9], v[2:3]
	v_pk_fma_f32 v[2:3], v[16:17], v[2:3], v[14:15]
	v_pk_mul_f32 v[6:7], v[6:7], v[38:39]
	v_add_f32_e32 v0, v2, v3
	v_pk_fma_f32 v[6:7], v[4:5], v[10:11], v[6:7] op_sel_hi:[0,1,1]
	v_pk_fma_f32 v[4:5], v[4:5], v[12:13], v[8:9] op_sel_hi:[0,1,1]
	v_add_f32_dpp v0, v0, v0 quad_perm:[1,0,3,2] row_mask:0xf bank_mask:0xf bound_ctrl:1
	v_pk_fma_f32 v[38:39], v[42:43], v[38:39], v[40:41]
	ds_read_b128 v[108:111], v88 offset:4096
	v_add_f32_dpp v0, v0, v0 quad_perm:[2,3,0,1] row_mask:0xf bank_mask:0xf bound_ctrl:1
	v_add_f32_e32 v97, v38, v39
	ds_read_b128 v[100:103], v88
	v_add_f32_dpp v0, v0, v0 row_half_mirror row_mask:0xf bank_mask:0xf bound_ctrl:1
	ds_read_b128 v[120:123], v88 offset:8192
	ds_read_b128 v[112:115], v88 offset:4352
	v_add_f32_dpp v0, v0, v0 row_ror:8 row_mask:0xf bank_mask:0xf bound_ctrl:1
	s_waitcnt lgkmcnt(10)
	v_pk_fma_f32 v[2:3], v[34:35], v[0:1], v[6:7] op_sel_hi:[1,0,1] neg_lo:[1,0,0] neg_hi:[1,0,0]
	v_pk_fma_f32 v[4:5], v[36:37], v[0:1], v[4:5] op_sel_hi:[1,0,1] neg_lo:[1,0,0] neg_hi:[1,0,0]
	s_waitcnt lgkmcnt(6)
	v_pk_mul_f32 v[8:9], v[26:27], v[2:3]
	v_pk_mul_f32 v[6:7], v[48:49], v[4:5]
	v_pk_mul_f32 v[10:11], v[18:19], v[2:3]
	v_pk_mul_f32 v[12:13], v[20:21], v[4:5]
	v_pk_fma_f32 v[2:3], v[46:47], v[2:3], v[6:7]
	v_pk_fma_f32 v[4:5], v[28:29], v[4:5], v[8:9]
	v_add_f32_e32 v98, v2, v3
	v_add_f32_e32 v2, v4, v5
	v_pk_fma_f32 v[8:9], v[86:87], v[24:25], v[12:13] op_sel_hi:[0,1,1]
	s_nop 0
	v_add_f32_dpp v0, v2, v2 quad_perm:[1,0,3,2] row_mask:0xf bank_mask:0xf bound_ctrl:1
	v_pk_fma_f32 v[6:7], v[86:87], v[22:23], v[10:11] op_sel_hi:[0,1,1]
	ds_read_b128 v[104:107], v88 offset:256
	v_add_f32_dpp v0, v0, v0 quad_perm:[2,3,0,1] row_mask:0xf bank_mask:0xf bound_ctrl:1
	ds_read_b128 v[128:131], v88 offset:8448
	ds_read_b128 v[124:127], v88 offset:4608
	v_add_f32_dpp v0, v0, v0 row_half_mirror row_mask:0xf bank_mask:0xf bound_ctrl:1
	ds_read_b128 v[116:119], v88 offset:512
	s_nop 0
	v_add_f32_dpp v0, v0, v0 row_ror:8 row_mask:0xf bank_mask:0xf bound_ctrl:1
	s_waitcnt lgkmcnt(9)
	v_pk_fma_f32 v[76:77], v[32:33], v[0:1], v[8:9] op_sel_hi:[1,0,1] neg_lo:[1,0,0] neg_hi:[1,0,0]
	v_pk_fma_f32 v[74:75], v[30:31], v[0:1], v[6:7] op_sel_hi:[1,0,1] neg_lo:[1,0,0] neg_hi:[1,0,0]
	s_waitcnt lgkmcnt(8)
	v_pk_mul_f32 v[2:3], v[52:53], v[76:77]
	s_nop 0
	v_pk_fma_f32 v[2:3], v[50:51], v[74:75], v[2:3]
	s_nop 0
	v_add_f32_e32 v99, v2, v3
	ds_write_b128 v91, v[96:99] offset:55296
	s_and_b32 s2, s26, 1
	s_mul_i32 s3, s2, 0x5400
	v_lshlrev_b32_e32 v91, 2, v87
	v_lshl_add_u32 v91, s2, 14, v91
	s_add_i32 s2, s3, 0
	v_add_u32_e32 v0, s2, v85
	v_add_u32_e32 v89, s2, v83
	v_add_u32_e32 v90, s96, v83
	s_add_i32 s96, s96, 0x3000
	s_cmp_eq_u32 s96, 0x1e800
	s_cselect_b32 s96, 0x20200, s96
	s_cmp_eq_u32 s96, 0x23200
	s_cselect_b32 s96, 0x12800, s96
	v_add_u32_e32 v88, s96, v83
	s_cmpk_eq_i32 s26, 0x110
	s_waitcnt lgkmcnt(0)
	s_barrier
	s_cbranch_scc0 .LBB0_1050
	s_setprio 0
